# P2 queue head: dropped the s_waitcnt vmcnt(0) drain before the pop barrier (it only waited for the previous item's output stores, which nothing in P2 reads)
# baseline (speedup 1.0000x reference)
; __global__ void __launch_bounds__(512, 2) mk_fwd(Params P, int ph_lo, int ph_hi) {
;     ...
;         for (;;) {
;             __syncthreads();
;             if (tid == 0) misc[0] = atomicAdd(ctr, 1u);
;             __syncthreads();
;             const int unit = (int)misc[0];
.LBB0_268:
	s_barrier
	s_and_saveexec_b64 s[4:5], s[8:9]
	s_cbranch_execz .LBB0_272
	s_mov_b64 s[10:11], exec
	v_mbcnt_lo_u32_b32 v2, s10, 0
	v_mbcnt_hi_u32_b32 v2, s11, v2
	v_cmp_eq_u32_e32 vcc, 0, v2
	s_and_saveexec_b64 s[6:7], vcc
	s_cbranch_execz .LBB0_271
	s_bcnt1_i32_b64 s10, s[10:11]
	v_mov_b32_e32 v3, s10
	global_atomic_add v3, v71, v3, s[22:23] sc0
